# v31 + sec 7.4: one static s_setprio 1 for waves 4-7 during the two S5 scan passes (no barriers inside; lets the raised wave's MFMA bursts overlap the partner's fmac stream)
# baseline (speedup 1.0000x reference)
; #define LAS __attribute__((address_space(3)))
; template <bool FULL>
; __device__ __forceinline__ void s5_pass(const Params& P, LAS unsigned char* lds, int bx, int tid_in) {
;     int tid = tid_in; asm volatile("" : "+v"(tid)); const int lane = tid & 63, wave = __builtin_amdgcn_readfirstlane(tid >> 6);
;     unsigned char* ws = P.ws;
;     const bf16_t* U = (const bf16_t*)(ws + WS_Q); bf16_t* YG = (bf16_t*)(ws + WS_V);
;     const float* AB = (const float*)(ws + WS_MISC + MISC_AB); const bf16_t* BBT = (const bf16_t*)(ws + WS_MISC + MISC_BBT); const bf16_t* CMT = (const bf16_t*)(ws + WS_MISC + MISC_CMT);
;     f32x4* SEG = (f32x4*)(ws + WS_MISC + MISC_SEG);
;     LAS unsigned char* hl = lds + wave * (32 * HROW);
;     const int r32 = lane & 31, hi = lane >> 5, l16 = lane & 15, kg = lane >> 4;
;     for (int task = bx * NWAVES + wave; task < 4096; task += NWAVES * (int)gridDim.x) {
;         const int g = task & 127, bp = (task >> 7) & 3, seg = task >> 9;
.LBB0_399:
	s_or_b64 exec, exec, s[4:5]
	v_mov_b32_e32 v0, v215
	s_barrier
	s_nop 0
	v_readfirstlane_b32 s5, v0
	s_ashr_i32 s4, s5, 6
	s_add_i32 s4, s4, s33
	s_cmpk_gt_i32 s4, 0xfff
	s_cbranch_scc1 .LBB0_408
	v_lshrrev_b32_e32 v2, 2, v0
	v_and_b32_e32 v2, 8, v2
	v_and_b32_e32 v3, 63, v0
	v_mov_b32_e32 v85, 0
	v_lshlrev_b32_e32 v84, 1, v2
	v_lshl_add_u64 v[86:87], s[16:17], 0, v[84:85]
	v_and_b32_e32 v4, 3, v0
	v_lshrrev_b32_e32 v7, 1, v0
	v_lshlrev_b32_e32 v84, 4, v3
	v_and_b32_e32 v1, 31, v0
	v_and_or_b32 v88, v7, 12, v4
	v_lshl_add_u64 v[4:5], s[30:31], 0, v[84:85]
	s_mov_b64 s[8:9], 0x1ec00000
	v_and_b32_e32 v84, 16, v7
	s_lshr_b32 s5, s5, 6
	v_lshlrev_b32_e32 v6, 1, v1
	v_and_b32_e32 v89, 4, v0
	v_lshl_add_u64 v[90:91], v[4:5], 0, s[8:9]
	v_lshlrev_b32_e32 v1, 4, v1
	v_lshl_add_u64 v[4:5], s[30:31], 0, v[84:85]
	s_mov_b64 s[8:9], 0x6810000
	v_lshlrev_b32_e32 v0, 12, v0
	v_lshl_add_u64 v[92:93], v[4:5], 0, s[8:9]
	v_and_b32_e32 v106, 0x4000, v0
	s_add_i32 s18, s33, s5
	s_cmp_lt_u32 s5, 4
	s_cbranch_scc1 .Ls5a_noprio
	s_setprio 1
.Ls5a_noprio:
	s_mul_i32 s50, s5, 9216
	s_add_i32 s52, s50, 8192
	v_lshlrev_b32_e32 v114, 4, v3
	s_mov_b32 s55, 0
	s_mov_b32 s9, 0
	v_lshlrev_b32_e32 v107, 2, v6
	v_lshlrev_b32_e32 v108, 1, v1
	v_lshlrev_b32_e32 v94, 1, v2
	s_mov_b64 s[10:11], 0x10000
	s_branch .LBB0_403

.LBB0_408:
	s_waitcnt vmcnt(0)
	s_setprio 0
	s_barrier
	s_and_saveexec_b64 s[4:5], s[24:25]
	s_cbranch_execz .LBB0_416
	v_mov_b32_e32 v0, 1
	buffer_wbl2 sc1
	s_waitcnt vmcnt(0)
	buffer_inv sc1
	global_atomic_add v0, v[136:137], v0, off sc0
	s_mul_i32 s8, s70, 5
	s_add_i32 s8, s8, -1
	s_waitcnt vmcnt(0)
	v_cmp_eq_u32_e32 vcc, s8, v0
	s_and_saveexec_b64 s[8:9], vcc
	s_cbranch_execz .LBB0_412
	s_mov_b64 s[10:11], exec
	v_mbcnt_lo_u32_b32 v0, s10, 0
	v_mbcnt_hi_u32_b32 v0, s11, v0
	v_cmp_eq_u32_e32 vcc, 0, v0
	s_and_b64 s[12:13], exec, vcc
	s_mov_b64 exec, s[12:13]
	s_cbranch_execz .LBB0_412
	s_bcnt1_i32_b64 s10, s[10:11]
	v_mov_b32_e32 v0, 0x1e828000
	v_mov_b32_e32 v1, s10
	global_atomic_add v0, v1, s[30:31] offset:2048

; __device__ __forceinline__ unsigned f2bf(float f) { unsigned u = __builtin_bit_cast(unsigned, f); return (u + 0x7fffu + ((u >> 16) & 1u)) >> 16; }
; template <bool FULL>
; __device__ __forceinline__ void s5_pass(const Params& P, LAS unsigned char* lds, int bx, int tid_in) {
;     ...
;     const int r32 = lane & 31, hi = lane >> 5, l16 = lane & 15, kg = lane >> 4;
;     for (int task = bx * NWAVES + wave; task < 4096; task += NWAVES * (int)gridDim.x) {
;         const int g = task & 127, bp = (task >> 7) & 3, seg = task >> 9;
;         if (!FULL && seg == 7) continue;
;         const float ar0 = AB[(g * 64 + r32) * 2], ai0 = AB[(g * 64 + r32) * 2 + 1], ar1 = AB[(g * 64 + 32 + r32) * 2], ai1 = AB[(g * 64 + 32 + r32) * 2 + 1];
;         bf16x8 bfr[4], cfr[4];
; #pragma unroll
;         for (int j = 0; j < 4; ++j) { bfr[j] = *(const bf16x8*)(BBT + ((g * 4 + j) * 32 + r32) * 16 + 8 * hi); if (FULL) cfr[j] = *(const bf16x8*)(CMT + (g * 16 + l16) * 128 + 32 * j + 8 * kg); }
;         bf16x8 dh, dl;
;         if (FULL) { const float d = P.in[20][g * 16 + l16]; const unsigned h16 = f2bf(d); const unsigned l16b = f2bf(d - __builtin_bit_cast(float, h16 << 16));
; #pragma unroll
;           for (int i = 0; i < 8; ++i) { const bool on = (kg < 2) && (8 * kg + i == l16); dh[i] = on ? (short)h16 : (short)0; dl[i] = on ? (short)l16b : (short)0; } }
;         const int m = r32, bsel = (m >> 2) & 1, tok = (m & 3) + 4 * (m >> 3);
;         const int tbeg = seg * S5_SEGLEN;
;         const bf16_t* u32p = U + ((size_t)(bp + 4 * bsel) * SEQ + tbeg + tok) * BR + g * 16 + 8 * hi;
;         const bf16_t* u16p = U + ((size_t)bp * SEQ + tbeg + l16) * BR + g * 16 + 8 * (kg & 1);
;         bf16_t* yp = YG + ((size_t)bp * SEQ + tbeg + 4 * kg) * BR + g * 16 + l16;
.LBB0_416:
	s_or_b64 exec, exec, s[4:5]
	v_mov_b32_e32 v0, v215
	s_barrier
	s_nop 0
	v_readfirstlane_b32 s5, v0
	s_ashr_i32 s4, s5, 6
	s_add_i32 s52, s4, s33
	s_cmpk_gt_i32 s52, 0xfff
	s_cbranch_scc1 .LBB0_427
	v_and_b32_e32 v1, 63, v0
	v_mov_b32_e32 v127, 0
	v_bfe_u32 v3, v0, 4, 2
	s_mulk_i32 s4, 0x2200
	v_lshlrev_b32_e32 v6, 4, v1
	v_mov_b32_e32 v7, v127
	s_lshr_b32 s40, s5, 6
	s_add_i32 s8, s4, 0
	v_lshlrev_b32_e32 v9, 3, v3
	v_lshl_add_u64 v[6:7], s[30:31], 0, v[6:7]
	s_mov_b64 s[4:5], 0x1ec00000
	v_and_b32_e32 v124, 15, v0
	v_bfe_u32 v5, v0, 5, 1
	v_lshl_add_u64 v[138:139], v[6:7], 0, s[4:5]
	v_or_b32_e32 v6, 1, v9
	v_lshlrev_b32_e32 v126, 4, v5
	v_cmp_eq_u32_e64 s[10:11], v6, v124
	v_or_b32_e32 v6, 2, v9
	v_lshl_add_u64 v[128:129], s[16:17], 0, v[126:127]
	v_and_b32_e32 v126, 48, v0
	v_cmp_eq_u32_e64 s[12:13], v6, v124
	v_or_b32_e32 v6, 3, v9
	v_lshl_add_u64 v[130:131], s[14:15], 0, v[126:127]
	v_cmp_eq_u32_e64 s[14:15], v6, v124
	v_or_b32_e32 v6, 4, v9
	v_lshlrev_b32_e32 v134, 2, v3
	v_add_u32_e32 v3, s8, v126
	v_cmp_eq_u32_e64 s[16:17], v6, v124
	v_or_b32_e32 v6, 5, v9
	v_lshlrev_b32_e32 v126, 1, v124
	v_lshrrev_b32_e32 v10, 1, v0
	v_cmp_eq_u32_e64 s[18:19], v6, v124
	v_or_b32_e32 v6, 6, v9
	v_lshl_add_u64 v[140:141], s[30:31], 0, v[126:127]
	v_and_b32_e32 v126, 16, v0
	v_and_b32_e32 v125, 31, v0
	v_and_b32_e32 v4, 3, v0
	v_cmp_eq_u32_e64 s[20:21], v6, v124
	v_or_b32_e32 v6, 7, v9
	v_lshl_add_u64 v[142:143], s[30:31], 0, v[126:127]
	v_and_b32_e32 v126, 16, v10
	v_lshlrev_b32_e32 v2, 3, v5
	v_lshlrev_b32_e32 v8, 7, v124
	v_cmp_gt_u32_e32 vcc, 32, v1
	v_and_b32_e32 v135, 4, v0
	v_and_or_b32 v132, v10, 12, v4
	v_and_b32_e32 v4, 8, v9
	v_cmp_lt_u32_e64 s[4:5], 31, v1
	v_lshl_add_u32 v1, v125, 2, s8
	v_cmp_eq_u32_e64 s[8:9], v9, v124
	v_cmp_eq_u32_e64 s[22:23], v6, v124
	v_mul_u32_u24_e32 v5, 0x1100, v5
	v_mul_u32_u24_e32 v9, 0x110, v124
	v_lshl_add_u64 v[6:7], s[30:31], 0, v[126:127]
	s_mov_b64 s[42:43], 0x6810000
	v_lshlrev_b32_e32 v0, 12, v0
	s_mov_b32 s41, 0
	v_lshlrev_b32_e32 v133, 1, v125
	s_and_b64 s[8:9], vcc, s[8:9]
	s_and_b64 s[10:11], vcc, s[10:11]
	s_and_b64 s[12:13], vcc, s[12:13]
	s_and_b64 s[14:15], vcc, s[14:15]
	s_and_b64 s[16:17], vcc, s[16:17]
	s_and_b64 s[18:19], vcc, s[18:19]
	s_and_b64 s[20:21], vcc, s[20:21]
	s_and_b64 s[22:23], vcc, s[22:23]
	s_add_i32 s33, s33, s40
	s_cmp_lt_u32 s40, 4
	s_cbranch_scc1 .Ls5b_noprio
	s_setprio 1
.Ls5b_noprio:
	s_mul_i32 s71, s40, 9216
	s_add_i32 s71, s71, 69632
	s_add_i32 s73, s71, 8192
	s_mov_b32 s77, 0
	s_mov_b32 s82, 0xffff0000
	s_mov_b32 s83, -1
	s_add_u32 s78, s30, 0x16800000
	s_addc_u32 s79, s31, 0
	s_add_u32 s80, s30, 0x1a800000
	s_addc_u32 s81, s31, 0
	v_and_b32_e32 v186, 63, v215
	v_lshlrev_b32_e32 v184, 4, v186
	v_and_b32_e32 v185, 3, v124
	v_lshrrev_b32_e32 v186, 2, v124
	v_lshl_add_u32 v185, v186, 3, v185
	v_lshlrev_b32_e32 v185, 4, v185
	v_and_b32_e32 v186, 16, v215
	v_lshl_add_u32 v185, v186, 5, v185
	v_and_b32_e32 v186, 7, v215
	v_mov_b32_e32 v214, 0x23000
	v_lshl_add_u32 v186, v186, 4, v214
	v_mov_b32_e32 v216, 0
	v_mov_b32_e32 v217, 0
	v_mov_b32_e32 v218, 0
	v_mov_b32_e32 v219, 0
	ds_write_b128 v186, v[216:219]
	s_waitcnt lgkmcnt(0)
	s_mov_b32 s84, 0x55555555
	s_mov_b32 s85, 0x55555555
	v_mov_b32_e32 v231, 0x01000504
	v_mov_b32_e32 v232, 0x03020706
	v_mov_b32_e32 v233, 0x05040100
	v_mov_b32_e32 v234, 0x07060302
	v_cndmask_b32_e64 v231, v231, v233, s[84:85]
	v_cndmask_b32_e64 v232, v232, v234, s[84:85]
	v_lshl_add_u64 v[144:145], v[6:7], 0, s[42:43]
	v_and_b32_e32 v172, 0x4000, v0
	v_lshlrev_b32_e32 v173, 1, v8
	s_movk_i32 s53, 0x7fff
	v_lshlrev_b32_e32 v146, 1, v2
	v_lshlrev_b32_e32 v148, 1, v4
	s_brev_b32 s54, 32
	s_mov_b32 s55, 0x5040100
	v_add_u32_e32 v174, v1, v5
	v_add_u32_e32 v226, 0x400, v174
	v_add_u32_e32 v227, 0x800, v174
	v_add_u32_e32 v228, 0xa00, v174
	v_add_u32_e32 v229, 0xc00, v174
	v_add_u32_e32 v230, 0xe00, v174
	v_add_u32_e32 v175, v3, v9
	s_mov_b32 s56, 0x16800000
	s_mov_b32 s57, 0x16801000
	s_mov_b32 s58, 0x16802000
	s_mov_b32 s59, 0x16803000
	s_mov_b32 s60, 0x1a800000
	s_mov_b32 s61, 0x1a801000
	s_mov_b64 s[42:43], 0x10000
	s_branch .LBB0_419

.LBB0_427:
	s_waitcnt vmcnt(0)
	s_setprio 0
	s_barrier
	s_and_saveexec_b64 s[4:5], s[24:25]
	s_cbranch_execz .LBB0_435
	v_mov_b32_e32 v0, 1
	buffer_wbl2 sc1
	s_waitcnt vmcnt(0)
	buffer_inv sc1
	global_atomic_add v0, v[136:137], v0, off sc0
	s_mul_i32 s8, s70, 6
	s_add_i32 s8, s8, -1
	s_waitcnt vmcnt(0)
	v_cmp_eq_u32_e32 vcc, s8, v0
	s_and_saveexec_b64 s[8:9], vcc
	s_cbranch_execz .LBB0_431
	s_mov_b64 s[10:11], exec
	v_mbcnt_lo_u32_b32 v0, s10, 0
	v_mbcnt_hi_u32_b32 v0, s11, v0
	v_cmp_eq_u32_e32 vcc, 0, v0
	s_and_b64 s[12:13], exec, vcc
	s_mov_b64 exec, s[12:13]
	s_cbranch_execz .LBB0_431
	s_bcnt1_i32_b64 s10, s[10:11]
	v_mov_b32_e32 v0, 0x1e828000
	v_mov_b32_e32 v1, s10
	global_atomic_add v0, v1, s[30:31] offset:2048
